# K=2816 skinny units (P5, P12): 4th step of each batch requested with the other three; P0 compression-bias dot product requested in one batch
# baseline (speedup 1.0000x reference)
; __device__ __forceinline__ void p0_prologue(const P0Args& a, LAS unsigned char* lds, int gw, int NGW, int wave, int lane) {
;     ...
;     for (int it = gw; it < 64 * 32; it += NGW) if ((it & 31) == 0) { const int ci = it >> 5, type = ci >> 5, chunk = ci & 31; float s = 0.f;
;         const float* wp = a.w_cmp + ((size_t)type * 2048 + chunk * 64) * 64 + lane; const float* pp = a.pe_cmp + type * 2048 + chunk * 64;
; #pragma unroll 16
;         for (int kk = 0; kk < 64; ++kk) s += pp[kk] * wp[(size_t)kk * 64];
;         ((float*)(ws + WS_CBIAS + 4096))[ci * 64 + lane] = s; }
.LBB0_207:
	s_add_u32 s20, s18, 0
	s_addc_u32 s21, s19, 0
	global_load_dword v84, v[6:7], off offset:-2048
	global_load_dword v85, v[6:7], off offset:-1792
	global_load_dword v86, v[6:7], off offset:-1536
	global_load_dword v87, v[6:7], off offset:-1280
	global_load_dword v88, v[6:7], off offset:-1024
	global_load_dword v89, v[6:7], off offset:-768
	global_load_dword v90, v[6:7], off offset:-512
	global_load_dword v91, v[6:7], off offset:-256
	global_load_dword v92, v[6:7], off
	global_load_dword v93, v[6:7], off offset:256
	global_load_dword v94, v[6:7], off offset:512
	global_load_dword v95, v[6:7], off offset:768
	global_load_dword v96, v[6:7], off offset:1024
	global_load_dword v97, v[6:7], off offset:1280
	global_load_dword v98, v[6:7], off offset:1536
	global_load_dword v99, v[6:7], off offset:1792
	global_load_dwordx4 v[100:103], v1, s[20:21]
	global_load_dwordx4 v[104:107], v1, s[20:21] offset:16
	global_load_dwordx4 v[108:111], v1, s[20:21] offset:32
	global_load_dwordx4 v[112:115], v1, s[20:21] offset:48
	v_lshl_add_u64 v[6:7], v[6:7], 0, s[4:5]
	s_add_u32 s20, s18, 64
	s_addc_u32 s21, s19, 0
	global_load_dword v116, v[6:7], off offset:-2048
	global_load_dword v117, v[6:7], off offset:-1792
	global_load_dword v118, v[6:7], off offset:-1536
	global_load_dword v119, v[6:7], off offset:-1280
	global_load_dword v120, v[6:7], off offset:-1024
	global_load_dword v121, v[6:7], off offset:-768
	global_load_dword v122, v[6:7], off offset:-512
	global_load_dword v123, v[6:7], off offset:-256
	global_load_dword v124, v[6:7], off
	global_load_dword v125, v[6:7], off offset:256
	global_load_dword v126, v[6:7], off offset:512
	global_load_dword v127, v[6:7], off offset:768
	global_load_dword v128, v[6:7], off offset:1024
	global_load_dword v129, v[6:7], off offset:1280
	global_load_dword v130, v[6:7], off offset:1536
	global_load_dword v131, v[6:7], off offset:1792
	global_load_dwordx4 v[132:135], v1, s[20:21]
	global_load_dwordx4 v[136:139], v1, s[20:21] offset:16
	global_load_dwordx4 v[140:143], v1, s[20:21] offset:32
	global_load_dwordx4 v[144:147], v1, s[20:21] offset:48
	v_lshl_add_u64 v[6:7], v[6:7], 0, s[4:5]
	s_add_u32 s20, s18, 128
	s_addc_u32 s21, s19, 0
	global_load_dword v148, v[6:7], off offset:-2048
	global_load_dword v149, v[6:7], off offset:-1792
	global_load_dword v150, v[6:7], off offset:-1536
	global_load_dword v151, v[6:7], off offset:-1280
	global_load_dword v152, v[6:7], off offset:-1024
	global_load_dword v153, v[6:7], off offset:-768
	global_load_dword v154, v[6:7], off offset:-512
	global_load_dword v155, v[6:7], off offset:-256
	global_load_dword v156, v[6:7], off
	global_load_dword v157, v[6:7], off offset:256
	global_load_dword v158, v[6:7], off offset:512
	global_load_dword v159, v[6:7], off offset:768
	global_load_dword v160, v[6:7], off offset:1024
	global_load_dword v161, v[6:7], off offset:1280
	global_load_dword v162, v[6:7], off offset:1536
	global_load_dword v163, v[6:7], off offset:1792
	global_load_dwordx4 v[164:167], v1, s[20:21]
	global_load_dwordx4 v[168:171], v1, s[20:21] offset:16
	global_load_dwordx4 v[172:175], v1, s[20:21] offset:32
	global_load_dwordx4 v[176:179], v1, s[20:21] offset:48
	v_lshl_add_u64 v[6:7], v[6:7], 0, s[4:5]
	s_add_u32 s20, s18, 192
	s_addc_u32 s21, s19, 0
	global_load_dword v180, v[6:7], off offset:-2048
	global_load_dword v181, v[6:7], off offset:-1792
	global_load_dword v182, v[6:7], off offset:-1536
	global_load_dword v183, v[6:7], off offset:-1280
	global_load_dword v184, v[6:7], off offset:-1024
	global_load_dword v185, v[6:7], off offset:-768
	global_load_dword v186, v[6:7], off offset:-512
	global_load_dword v187, v[6:7], off offset:-256
	global_load_dword v188, v[6:7], off
	global_load_dword v189, v[6:7], off offset:256
	global_load_dword v190, v[6:7], off offset:512
	global_load_dword v191, v[6:7], off offset:768
	global_load_dword v192, v[6:7], off offset:1024
	global_load_dword v193, v[6:7], off offset:1280
	global_load_dword v194, v[6:7], off offset:1536
	global_load_dword v195, v[6:7], off offset:1792
	global_load_dwordx4 v[196:199], v1, s[20:21]
	global_load_dwordx4 v[200:203], v1, s[20:21] offset:16
	global_load_dwordx4 v[204:207], v1, s[20:21] offset:32
	global_load_dwordx4 v[208:211], v1, s[20:21] offset:48
	v_lshl_add_u64 v[6:7], v[6:7], 0, s[4:5]
	s_waitcnt vmcnt(60)
	v_fmac_f32_e32 v0, v100, v84
	v_fmac_f32_e32 v0, v101, v85
	v_fmac_f32_e32 v0, v102, v86
	v_fmac_f32_e32 v0, v103, v87
	v_fmac_f32_e32 v0, v104, v88
	v_fmac_f32_e32 v0, v105, v89
	v_fmac_f32_e32 v0, v106, v90
	v_fmac_f32_e32 v0, v107, v91
	v_fmac_f32_e32 v0, v108, v92
	v_fmac_f32_e32 v0, v109, v93
	v_fmac_f32_e32 v0, v110, v94
	v_fmac_f32_e32 v0, v111, v95
	v_fmac_f32_e32 v0, v112, v96
	v_fmac_f32_e32 v0, v113, v97
	v_fmac_f32_e32 v0, v114, v98
	v_fmac_f32_e32 v0, v115, v99
	s_waitcnt vmcnt(40)
	v_fmac_f32_e32 v0, v132, v116
	v_fmac_f32_e32 v0, v133, v117
	v_fmac_f32_e32 v0, v134, v118
	v_fmac_f32_e32 v0, v135, v119
	v_fmac_f32_e32 v0, v136, v120
	v_fmac_f32_e32 v0, v137, v121
	v_fmac_f32_e32 v0, v138, v122
	v_fmac_f32_e32 v0, v139, v123
	v_fmac_f32_e32 v0, v140, v124
	v_fmac_f32_e32 v0, v141, v125
	v_fmac_f32_e32 v0, v142, v126
	v_fmac_f32_e32 v0, v143, v127
	v_fmac_f32_e32 v0, v144, v128
	v_fmac_f32_e32 v0, v145, v129
	v_fmac_f32_e32 v0, v146, v130
	v_fmac_f32_e32 v0, v147, v131
	s_waitcnt vmcnt(20)
	v_fmac_f32_e32 v0, v164, v148
	v_fmac_f32_e32 v0, v165, v149
	v_fmac_f32_e32 v0, v166, v150
	v_fmac_f32_e32 v0, v167, v151
	v_fmac_f32_e32 v0, v168, v152
	v_fmac_f32_e32 v0, v169, v153
	v_fmac_f32_e32 v0, v170, v154
	v_fmac_f32_e32 v0, v171, v155
	v_fmac_f32_e32 v0, v172, v156
	v_fmac_f32_e32 v0, v173, v157
	v_fmac_f32_e32 v0, v174, v158
	v_fmac_f32_e32 v0, v175, v159
	v_fmac_f32_e32 v0, v176, v160
	v_fmac_f32_e32 v0, v177, v161
	v_fmac_f32_e32 v0, v178, v162
	v_fmac_f32_e32 v0, v179, v163
	s_waitcnt vmcnt(0)
	v_fmac_f32_e32 v0, v196, v180
	v_fmac_f32_e32 v0, v197, v181
	v_fmac_f32_e32 v0, v198, v182
	v_fmac_f32_e32 v0, v199, v183
	v_fmac_f32_e32 v0, v200, v184
	v_fmac_f32_e32 v0, v201, v185
	v_fmac_f32_e32 v0, v202, v186
	v_fmac_f32_e32 v0, v203, v187
	v_fmac_f32_e32 v0, v204, v188
	v_fmac_f32_e32 v0, v205, v189
	v_fmac_f32_e32 v0, v206, v190
	v_fmac_f32_e32 v0, v207, v191
	v_fmac_f32_e32 v0, v208, v192
	v_fmac_f32_e32 v0, v209, v193
	v_fmac_f32_e32 v0, v210, v194
	v_fmac_f32_e32 v0, v211, v195
	v_lshl_or_b32 v6, s17, 1, v4
	v_ashrrev_i32_e32 v7, 31, v6
	v_lshl_add_u64 v[6:7], v[6:7], 2, s[0:1]
	global_store_dword v[6:7], v0, off
	s_branch .LBB0_204

; template <bool FIRST> __device__ __forceinline__ void skinny_resid(const bf16* __restrict__ A, const bf16* __restrict__ Bt, int K, const float* xs, bf16* XB, float* SS, int u, LAS unsigned char* lds, int tid) {
;     ...
;     for (int j0 = 0; j0 < nj; j0 += 4) { bf16x8 af[4], bf[4][4];
; #pragma unroll
;         for (int s = 0; s < 4; ++s) { const int j = (j0 + s < nj) ? j0 + s : nj - 1;
;             af[s] = *(const bf16x8*)(ap + 256 * j);
; #pragma unroll
;             for (int ct = 0; ct < 4; ++ct) bf[s][ct] = *(const bf16x8*)(bp + (size_t)16 * ct * K + 256 * j); }
;         __builtin_amdgcn_sched_barrier(0);
; #pragma unroll
;         for (int s = 0; s < 4; ++s) if (j0 + s < nj) {
; #pragma unroll
;             for (int ct = 0; ct < 4; ++ct) acc[ct] = __builtin_amdgcn_mfma_f32_16x16x32_bf16(af[s], bf[s][ct], acc[ct], 0, 0, 0); }
;         __builtin_amdgcn_sched_barrier(0); }
.LBB0_1310:
	v_lshl_add_u64 v[36:37], v[26:27], 0, v[20:21]
	v_add_co_u32_e32 v72, vcc, s30, v36
	v_lshl_add_u64 v[64:65], v[26:27], 0, v[28:29]
	s_nop 0
	v_addc_co_u32_e32 v73, vcc, 0, v37, vcc
	v_add_co_u32_e32 v80, vcc, s31, v36
	s_add_i32 s18, s40, 7
	s_nop 0
	v_addc_co_u32_e32 v81, vcc, 0, v37, vcc
	v_add_co_u32_e32 v88, vcc, s34, v36
	s_cmp_gt_u32 s18, 10
	s_nop 0
	v_addc_co_u32_e32 v89, vcc, 0, v37, vcc
	v_add_co_u32_e32 v92, vcc, s35, v36
	s_nop 1
	v_addc_co_u32_e32 v93, vcc, 0, v37, vcc
	global_load_dwordx4 v[36:39], v[64:65], off offset:-512
	global_load_dwordx4 v[40:43], v[64:65], off
	global_load_dwordx4 v[44:47], v[80:81], off
	global_load_dwordx4 v[48:51], v[80:81], off offset:512
	global_load_dwordx4 v[52:55], v[92:93], off
	global_load_dwordx4 v[56:59], v[92:93], off offset:512
	global_load_dwordx4 v[60:63], v[72:73], off
	s_nop 0
	global_load_dwordx4 v[64:67], v[64:65], off offset:512
	s_nop 0
	global_load_dwordx4 v[68:71], v[72:73], off offset:512
	s_nop 0
	global_load_dwordx4 v[72:75], v[72:73], off offset:1024
	s_nop 0
	global_load_dwordx4 v[76:79], v[88:89], off
	s_nop 0
	global_load_dwordx4 v[80:83], v[80:81], off offset:1024
	s_nop 0
	global_load_dwordx4 v[84:87], v[88:89], off offset:512
	s_nop 0
	global_load_dwordx4 v[88:91], v[88:89], off offset:1024
	s_nop 0
	global_load_dwordx4 v[92:95], v[92:93], off offset:1024
	s_min_u32 s98, s18, 10
	s_lshl_b32 s98, s98, 9
	s_mov_b32 s99, 0
	s_mov_b32 s100, 0x16000
	s_mov_b32 s101, 0
	s_cmp_gt_u32 s18, 10
	v_lshl_add_u64 v[224:225], v[22:23], 0, s[98:99]
	v_lshl_add_u64 v[226:227], v[24:25], 0, s[98:99]
	global_load_dwordx4 v[204:207], v[224:225], off
	v_lshl_add_u64 v[228:229], v[226:227], 0, s[100:101]
	global_load_dwordx4 v[208:211], v[226:227], off
	v_lshl_add_u64 v[230:231], v[228:229], 0, s[100:101]
	global_load_dwordx4 v[212:215], v[228:229], off
	v_lshl_add_u64 v[232:233], v[230:231], 0, s[100:101]
	global_load_dwordx4 v[216:219], v[230:231], off
	global_load_dwordx4 v[220:223], v[232:233], off
	s_waitcnt vmcnt(13)
	v_mfma_f32_16x16x32_bf16 v[12:15], v[36:39], v[60:63], v[12:15]
	v_mfma_f32_16x16x32_bf16 v[8:11], v[36:39], v[44:47], v[8:11]
	s_waitcnt vmcnt(9)
	v_mfma_f32_16x16x32_bf16 v[4:7], v[36:39], v[76:79], v[4:7]
	v_mfma_f32_16x16x32_bf16 v[0:3], v[36:39], v[52:55], v[0:3]
	v_mfma_f32_16x16x32_bf16 v[12:15], v[40:43], v[68:71], v[12:15]
	v_mfma_f32_16x16x32_bf16 v[8:11], v[40:43], v[48:51], v[8:11]
	s_waitcnt vmcnt(7)
	v_mfma_f32_16x16x32_bf16 v[4:7], v[40:43], v[84:87], v[4:7]
	v_mfma_f32_16x16x32_bf16 v[0:3], v[40:43], v[56:59], v[0:3]
	v_mfma_f32_16x16x32_bf16 v[12:15], v[64:67], v[72:75], v[12:15]
	v_mfma_f32_16x16x32_bf16 v[8:11], v[64:67], v[80:83], v[8:11]
	s_waitcnt vmcnt(6)
	v_mfma_f32_16x16x32_bf16 v[4:7], v[64:67], v[88:91], v[4:7]
	s_waitcnt vmcnt(5)
	v_mfma_f32_16x16x32_bf16 v[0:3], v[64:67], v[92:95], v[0:3]
	s_cbranch_scc1 .LBB0_1309
	s_waitcnt vmcnt(3)
	v_mfma_f32_16x16x32_bf16 v[12:15], v[204:207], v[208:211], v[12:15]
	s_waitcnt vmcnt(2)
	v_mfma_f32_16x16x32_bf16 v[8:11], v[204:207], v[212:215], v[8:11]
	s_waitcnt vmcnt(1)
	v_mfma_f32_16x16x32_bf16 v[4:7], v[204:207], v[216:219], v[4:7]
	s_waitcnt vmcnt(0)
	v_mfma_f32_16x16x32_bf16 v[0:3], v[204:207], v[220:223], v[0:3]
	s_branch .LBB0_1309

; template <bool FIRST> __device__ __forceinline__ void skinny_resid(const bf16* __restrict__ A, const bf16* __restrict__ Bt, int K, const float* xs, bf16* XB, float* SS, int u, LAS unsigned char* lds, int tid) {
;     ...
;     for (int j0 = 0; j0 < nj; j0 += 4) { bf16x8 af[4], bf[4][4];
; #pragma unroll
;         for (int s = 0; s < 4; ++s) { const int j = (j0 + s < nj) ? j0 + s : nj - 1;
;             af[s] = *(const bf16x8*)(ap + 256 * j);
; #pragma unroll
;             for (int ct = 0; ct < 4; ++ct) bf[s][ct] = *(const bf16x8*)(bp + (size_t)16 * ct * K + 256 * j); }
;         __builtin_amdgcn_sched_barrier(0);
; #pragma unroll
;         for (int s = 0; s < 4; ++s) if (j0 + s < nj) {
; #pragma unroll
;             for (int ct = 0; ct < 4; ++ct) acc[ct] = __builtin_amdgcn_mfma_f32_16x16x32_bf16(af[s], bf[s][ct], acc[ct], 0, 0, 0); }
;         __builtin_amdgcn_sched_barrier(0); }
.LBB0_3163:
	v_lshl_add_u64 v[34:35], v[26:27], 0, v[20:21]
	v_add_co_u32_e32 v96, vcc, s20, v34
	v_lshl_add_u64 v[94:95], v[26:27], 0, v[28:29]
	s_nop 0
	v_addc_co_u32_e32 v97, vcc, 0, v35, vcc
	v_add_co_u32_e32 v98, vcc, s21, v34
	s_add_i32 s6, s26, 7
	s_nop 0
	v_addc_co_u32_e32 v99, vcc, 0, v35, vcc
	v_add_co_u32_e32 v100, vcc, s23, v34
	s_cmp_gt_u32 s6, 10
	s_nop 0
	v_addc_co_u32_e32 v101, vcc, 0, v35, vcc
	v_add_co_u32_e32 v102, vcc, s24, v34
	s_nop 1
	v_addc_co_u32_e32 v103, vcc, 0, v35, vcc
	global_load_dwordx4 v[34:37], v[94:95], off offset:-512
	global_load_dwordx4 v[38:41], v[94:95], off
	global_load_dwordx4 v[42:45], v[98:99], off
	global_load_dwordx4 v[46:49], v[98:99], off offset:512
	global_load_dwordx4 v[50:53], v[102:103], off
	global_load_dwordx4 v[54:57], v[102:103], off offset:512
	global_load_dwordx4 v[58:61], v[96:97], off
	global_load_dwordx4 v[62:65], v[94:95], off offset:512
	global_load_dwordx4 v[66:69], v[96:97], off offset:512
	global_load_dwordx4 v[70:73], v[96:97], off offset:1024
	global_load_dwordx4 v[74:77], v[100:101], off
	global_load_dwordx4 v[78:81], v[98:99], off offset:1024
	global_load_dwordx4 v[82:85], v[100:101], off offset:512
	global_load_dwordx4 v[86:89], v[100:101], off offset:1024
	global_load_dwordx4 v[90:93], v[102:103], off offset:1024
	s_min_u32 s98, s6, 10
	s_lshl_b32 s98, s98, 9
	s_mov_b32 s99, 0
	s_mov_b32 s100, 0x16000
	s_mov_b32 s101, 0
	s_cmp_gt_u32 s6, 10
	v_lshl_add_u64 v[224:225], v[22:23], 0, s[98:99]
	v_lshl_add_u64 v[226:227], v[24:25], 0, s[98:99]
	global_load_dwordx4 v[204:207], v[224:225], off
	v_lshl_add_u64 v[228:229], v[226:227], 0, s[100:101]
	global_load_dwordx4 v[208:211], v[226:227], off
	v_lshl_add_u64 v[230:231], v[228:229], 0, s[100:101]
	global_load_dwordx4 v[212:215], v[228:229], off
	v_lshl_add_u64 v[232:233], v[230:231], 0, s[100:101]
	global_load_dwordx4 v[216:219], v[230:231], off
	global_load_dwordx4 v[220:223], v[232:233], off
	s_waitcnt vmcnt(13)
	v_mfma_f32_16x16x32_bf16 v[12:15], v[34:37], v[58:61], v[12:15]
	v_mfma_f32_16x16x32_bf16 v[8:11], v[34:37], v[42:45], v[8:11]
	s_waitcnt vmcnt(9)
	v_mfma_f32_16x16x32_bf16 v[4:7], v[34:37], v[74:77], v[4:7]
	v_mfma_f32_16x16x32_bf16 v[0:3], v[34:37], v[50:53], v[0:3]
	v_mfma_f32_16x16x32_bf16 v[12:15], v[38:41], v[66:69], v[12:15]
	v_mfma_f32_16x16x32_bf16 v[8:11], v[38:41], v[46:49], v[8:11]
	s_waitcnt vmcnt(7)
	v_mfma_f32_16x16x32_bf16 v[4:7], v[38:41], v[82:85], v[4:7]
	v_mfma_f32_16x16x32_bf16 v[0:3], v[38:41], v[54:57], v[0:3]
	v_mfma_f32_16x16x32_bf16 v[12:15], v[62:65], v[70:73], v[12:15]
	v_mfma_f32_16x16x32_bf16 v[8:11], v[62:65], v[78:81], v[8:11]
	s_waitcnt vmcnt(6)
	v_mfma_f32_16x16x32_bf16 v[4:7], v[62:65], v[86:89], v[4:7]
	s_waitcnt vmcnt(5)
	v_mfma_f32_16x16x32_bf16 v[0:3], v[62:65], v[90:93], v[0:3]
	s_cbranch_scc1 .LBB0_3162
	s_waitcnt vmcnt(3)
	v_mfma_f32_16x16x32_bf16 v[12:15], v[204:207], v[208:211], v[12:15]
	s_waitcnt vmcnt(2)
	v_mfma_f32_16x16x32_bf16 v[8:11], v[204:207], v[212:215], v[8:11]
	s_waitcnt vmcnt(1)
	v_mfma_f32_16x16x32_bf16 v[4:7], v[204:207], v[216:219], v[4:7]
	s_waitcnt vmcnt(0)
	v_mfma_f32_16x16x32_bf16 v[0:3], v[204:207], v[220:223], v[0:3]
	s_branch .LBB0_3162
